# speedup vs baseline: 1.0081x; 1.0029x over previous
; __device__ __forceinline__ unsigned f2bf(float f) { unsigned u = __builtin_bit_cast(unsigned, f); return (u + 0x7fffu + ((u >> 16) & 1u)) >> 16; }
; #define a (*get_args())
; __device__ __forceinline__ void phase_prologue(KArgs ap, LAS unsigned char* lds, const Ctx cx) {
;     ...
;         bf16_t* BT = (bf16_t*)(tb + TAB_BT); bf16_t* CT = (bf16_t*)(tb + TAB_CT);
;         const float* bre = a.in[I_B_RE] + ((size_t)(l * 32 + g) * 64 + p) * 16; const float* bim = a.in[I_B_IM] + ((size_t)(l * 32 + g) * 64 + p) * 16;
;         for (int h = 0; h < 16; ++h) {
;             const float br = bre[h], bi = bim[h];
;             ((float*)(tb + TAB_BF))[((g * 64 + p) * 16 + h) * 2] = cre * br - cim * bi; ((float*)(tb + TAB_BF))[((g * 64 + p) * 16 + h) * 2 + 1] = cre * bi + cim * br;
;             BT[(g * 128 + p) * 16 + h] = (bf16_t)f2bf(cre * br - cim * bi);
;             BT[(g * 128 + 64 + p) * 16 + h] = (bf16_t)f2bf(cre * bi + cim * br);
;             CT[(g * 16 + h) * 128 + p] = (bf16_t)f2bf(a.in[I_C_RE][((size_t)(l * 32 + g) * 16 + h) * 64 + p]);
;             CT[(g * 16 + h) * 128 + 64 + p] = (bf16_t)f2bf(-a.in[I_C_IM][((size_t)(l * 32 + g) * 16 + h) * 64 + p]);
;         }
.LBB0_912:
	v_lshl_add_u64 v[114:115], v[16:17], 0, v[4:5]
	v_lshl_add_u64 v[116:117], v[14:15], 0, v[4:5]
	v_lshl_add_u64 v[118:119], v[24:25], 0, v[4:5]
	v_lshl_add_u64 v[120:121], v[2:3], 0, v[4:5]
	global_load_dword v50, v[114:115], off offset:-4
	global_load_dword v66, v[116:117], off offset:-4
	global_load_dword v51, v[114:115], off offset:0
	global_load_dword v67, v[116:117], off offset:0
	global_load_dword v82, v[118:119], off offset:0
	global_load_dword v98, v[120:121], off offset:0
	global_load_dword v83, v[118:119], off offset:256
	global_load_dword v99, v[120:121], off offset:256
	global_load_dword v52, v[114:115], off offset:4
	global_load_dword v68, v[116:117], off offset:4
	global_load_dword v53, v[114:115], off offset:8
	global_load_dword v69, v[116:117], off offset:8
	global_load_dword v84, v[118:119], off offset:512
	global_load_dword v100, v[120:121], off offset:512
	global_load_dword v85, v[118:119], off offset:768
	global_load_dword v101, v[120:121], off offset:768
	global_load_dword v54, v[114:115], off offset:12
	global_load_dword v70, v[116:117], off offset:12
	global_load_dword v55, v[114:115], off offset:16
	global_load_dword v71, v[116:117], off offset:16
	global_load_dword v86, v[118:119], off offset:1024
	global_load_dword v102, v[120:121], off offset:1024
	global_load_dword v87, v[118:119], off offset:1280
	global_load_dword v103, v[120:121], off offset:1280
	global_load_dword v56, v[114:115], off offset:20
	global_load_dword v72, v[116:117], off offset:20
	global_load_dword v57, v[114:115], off offset:24
	global_load_dword v73, v[116:117], off offset:24
	global_load_dword v88, v[118:119], off offset:1536
	global_load_dword v104, v[120:121], off offset:1536
	global_load_dword v89, v[118:119], off offset:1792
	global_load_dword v105, v[120:121], off offset:1792
	global_load_dword v58, v[114:115], off offset:28
	global_load_dword v74, v[116:117], off offset:28
	global_load_dword v59, v[114:115], off offset:32
	global_load_dword v75, v[116:117], off offset:32
	global_load_dword v90, v[118:119], off offset:2048
	global_load_dword v106, v[120:121], off offset:2048
	global_load_dword v91, v[118:119], off offset:2304
	global_load_dword v107, v[120:121], off offset:2304
	global_load_dword v60, v[114:115], off offset:36
	global_load_dword v76, v[116:117], off offset:36
	global_load_dword v61, v[114:115], off offset:40
	global_load_dword v77, v[116:117], off offset:40
	global_load_dword v92, v[118:119], off offset:2560
	global_load_dword v108, v[120:121], off offset:2560
	global_load_dword v93, v[118:119], off offset:2816
	global_load_dword v109, v[120:121], off offset:2816
	global_load_dword v62, v[114:115], off offset:44
	global_load_dword v78, v[116:117], off offset:44
	global_load_dword v63, v[114:115], off offset:48
	global_load_dword v79, v[116:117], off offset:48
	global_load_dword v94, v[118:119], off offset:3072
	global_load_dword v110, v[120:121], off offset:3072
	global_load_dword v95, v[118:119], off offset:3328
	global_load_dword v111, v[120:121], off offset:3328
	global_load_dword v64, v[114:115], off offset:52
	global_load_dword v80, v[116:117], off offset:52
	global_load_dword v65, v[114:115], off offset:56
	global_load_dword v81, v[116:117], off offset:56
	global_load_dword v96, v[118:119], off offset:3584
	global_load_dword v112, v[120:121], off offset:3584
	global_load_dword v97, v[118:119], off offset:3840
	global_load_dword v113, v[120:121], off offset:3840
	s_waitcnt vmcnt(0)
	v_lshl_add_u64 v[30:31], v[16:17], 0, v[4:5]
	v_lshl_add_u64 v[28:29], v[14:15], 0, v[4:5]
	v_mov_b32_e32 v32, v50
	v_mov_b32_e32 v34, v66
	v_lshl_add_u64 v[36:37], v[18:19], 0, v[10:11]
	v_add_co_u32_e32 v36, vcc, s4, v36
	v_lshl_add_u64 v[14:15], v[14:15], 0, 8
	s_nop 0
	v_addc_co_u32_e32 v37, vcc, 0, v37, vcc
	v_lshl_add_u64 v[16:17], v[16:17], 0, 8
	v_lshl_add_u64 v[18:19], v[18:19], 0, 16
	v_pk_mul_f32 v[32:33], v[12:13], v[32:33] op_sel_hi:[1,0]
	s_nop 0
	v_pk_fma_f32 v[38:39], v[6:7], v[34:35], v[32:33] op_sel_hi:[1,0,1] neg_lo:[0,0,1] neg_hi:[0,0,1]
	v_pk_fma_f32 v[32:33], v[6:7], v[34:35], v[32:33] op_sel_hi:[1,0,1]
	s_nop 0
	v_mov_b32_e32 v39, v33
	global_store_dwordx2 v[36:37], v[38:39], off
	v_mov_b32_e32 v32, v51
	v_mov_b32_e32 v34, v67
	v_lshl_add_u64 v[28:29], v[24:25], 0, v[4:5]
	v_lshl_add_u64 v[30:31], v[2:3], 0, v[4:5]
	v_mov_b32_e32 v27, v82
	v_mov_b32_e32 v39, v98
	v_bfe_u32 v48, v33, 16, 1
	v_lshl_add_u64 v[2:3], v[2:3], 0, s[0:1]
	v_lshl_add_u64 v[24:25], v[24:25], 0, s[0:1]
	v_pk_mul_f32 v[40:41], v[12:13], v[32:33] op_sel_hi:[1,0]
	s_nop 0
	v_pk_fma_f32 v[42:43], v[6:7], v[34:35], v[40:41] op_sel_hi:[1,0,1] neg_lo:[0,0,1] neg_hi:[0,0,1]
	v_pk_fma_f32 v[34:35], v[6:7], v[34:35], v[40:41] op_sel_hi:[1,0,1]
	v_add3_u32 v33, v33, v48, s5
	v_mov_b32_e32 v43, v35
	global_store_dwordx2 v[36:37], v[42:43], off offset:8
	v_mov_b32_e32 v32, v99
	v_mov_b32_e32 v34, v83
	v_lshl_add_u64 v[28:29], v[20:21], 0, v[10:11]
	v_add_co_u32_e32 v28, vcc, s6, v28
	v_lshl_add_u64 v[30:31], v[22:23], 0, v[10:11]
	s_nop 0
	v_addc_co_u32_e32 v29, vcc, 0, v29, vcc
	v_bfe_u32 v43, v38, 16, 1
	v_add_u32_e32 v36, s13, v1
	v_add_co_u32_e32 v30, vcc, s6, v30
	v_add3_u32 v38, v38, v43, s5
	s_nop 0
	v_addc_co_u32_e32 v31, vcc, 0, v31, vcc
	v_ashrrev_i32_e32 v37, 31, v36
	v_add_u32_e32 v40, 64, v36
	global_store_short_d16_hi v[28:29], v38, off
	global_store_short_d16_hi v[30:31], v33, off
	v_bfe_u32 v33, v27, 16, 1
	v_xor_b32_e32 v38, 0x80000000, v39
	v_add_u32_e32 v44, 0x80, v36
	v_add_u32_e32 v46, 0xc0, v36
	v_lshl_add_u64 v[36:37], v[36:37], 1, v[8:9]
	v_ashrrev_i32_e32 v41, 31, v40
	v_add3_u32 v27, v27, v33, s5
	v_bfe_u32 v33, v38, 16, 1
; __device__ __forceinline__ unsigned f2bf(float f) { unsigned u = __builtin_bit_cast(unsigned, f); return (u + 0x7fffu + ((u >> 16) & 1u)) >> 16; }
; #define a (*get_args())
; __device__ __forceinline__ void phase_prologue(KArgs ap, LAS unsigned char* lds, const Ctx cx) {
;     ...
;         for (int h = 0; h < 16; ++h) {
;             const float br = bre[h], bi = bim[h];
;             ((float*)(tb + TAB_BF))[((g * 64 + p) * 16 + h) * 2] = cre * br - cim * bi; ((float*)(tb + TAB_BF))[((g * 64 + p) * 16 + h) * 2 + 1] = cre * bi + cim * br;
;             BT[(g * 128 + p) * 16 + h] = (bf16_t)f2bf(cre * br - cim * bi);
;             BT[(g * 128 + 64 + p) * 16 + h] = (bf16_t)f2bf(cre * bi + cim * br);
;             CT[(g * 16 + h) * 128 + p] = (bf16_t)f2bf(a.in[I_C_RE][((size_t)(l * 32 + g) * 16 + h) * 64 + p]);
;             CT[(g * 16 + h) * 128 + 64 + p] = (bf16_t)f2bf(-a.in[I_C_IM][((size_t)(l * 32 + g) * 16 + h) * 64 + p]);
;         }
	v_lshl_add_u64 v[40:41], v[40:41], 1, v[8:9]
	global_store_short_d16_hi v[36:37], v27, off
	v_add3_u32 v27, v38, v33, s5
	v_bfe_u32 v33, v42, 16, 1
	v_bfe_u32 v36, v35, 16, 1
	global_store_short_d16_hi v[40:41], v27, off
	v_add3_u32 v27, v42, v33, s5
	v_ashrrev_i32_e32 v45, 31, v44
	v_add3_u32 v33, v35, v36, s5
	global_store_short_d16_hi v[28:29], v27, off offset:2
	global_store_short_d16_hi v[30:31], v33, off offset:2
	s_addk_i32 s13, 0x100
	v_ashrrev_i32_e32 v47, 31, v46
	v_lshl_add_u64 v[44:45], v[44:45], 1, v[8:9]
	v_lshl_add_u64 v[20:21], v[20:21], 0, 4
	v_lshl_add_u64 v[22:23], v[22:23], 0, 4
	v_lshl_add_u64 v[46:47], v[46:47], 1, v[8:9]
	v_xor_b32_e32 v28, 0x80000000, v32
	v_bfe_u32 v27, v34, 16, 1
	v_add3_u32 v27, v34, v27, s5
	v_bfe_u32 v29, v28, 16, 1
	global_store_short_d16_hi v[44:45], v27, off
	v_add3_u32 v27, v28, v29, s5
	global_store_short_d16_hi v[46:47], v27, off
	v_lshl_add_u64 v[30:31], v[16:17], 0, v[4:5]
	v_lshl_add_u64 v[28:29], v[14:15], 0, v[4:5]
	v_mov_b32_e32 v32, v52
	v_mov_b32_e32 v34, v68
	v_lshl_add_u64 v[36:37], v[18:19], 0, v[10:11]
	v_add_co_u32_e32 v36, vcc, s4, v36
	v_lshl_add_u64 v[14:15], v[14:15], 0, 8
	s_nop 0
	v_addc_co_u32_e32 v37, vcc, 0, v37, vcc
	v_lshl_add_u64 v[16:17], v[16:17], 0, 8
	v_lshl_add_u64 v[18:19], v[18:19], 0, 16
	v_pk_mul_f32 v[32:33], v[12:13], v[32:33] op_sel_hi:[1,0]
	s_nop 0
	v_pk_fma_f32 v[38:39], v[6:7], v[34:35], v[32:33] op_sel_hi:[1,0,1] neg_lo:[0,0,1] neg_hi:[0,0,1]
	v_pk_fma_f32 v[32:33], v[6:7], v[34:35], v[32:33] op_sel_hi:[1,0,1]
	s_nop 0
	v_mov_b32_e32 v39, v33
	global_store_dwordx2 v[36:37], v[38:39], off
	v_mov_b32_e32 v32, v53
	v_mov_b32_e32 v34, v69
	v_lshl_add_u64 v[28:29], v[24:25], 0, v[4:5]
	v_lshl_add_u64 v[30:31], v[2:3], 0, v[4:5]
	v_mov_b32_e32 v27, v84
	v_mov_b32_e32 v39, v100
	v_bfe_u32 v48, v33, 16, 1
	v_lshl_add_u64 v[2:3], v[2:3], 0, s[0:1]
	v_lshl_add_u64 v[24:25], v[24:25], 0, s[0:1]
	v_pk_mul_f32 v[40:41], v[12:13], v[32:33] op_sel_hi:[1,0]
	s_nop 0
	v_pk_fma_f32 v[42:43], v[6:7], v[34:35], v[40:41] op_sel_hi:[1,0,1] neg_lo:[0,0,1] neg_hi:[0,0,1]
	v_pk_fma_f32 v[34:35], v[6:7], v[34:35], v[40:41] op_sel_hi:[1,0,1]
	v_add3_u32 v33, v33, v48, s5
	v_mov_b32_e32 v43, v35
	global_store_dwordx2 v[36:37], v[42:43], off offset:8
	v_mov_b32_e32 v32, v101
	v_mov_b32_e32 v34, v85
	v_lshl_add_u64 v[28:29], v[20:21], 0, v[10:11]
	v_add_co_u32_e32 v28, vcc, s6, v28
	v_lshl_add_u64 v[30:31], v[22:23], 0, v[10:11]
	s_nop 0
	v_addc_co_u32_e32 v29, vcc, 0, v29, vcc
	v_bfe_u32 v43, v38, 16, 1
	v_add_u32_e32 v36, s13, v1
	v_add_co_u32_e32 v30, vcc, s6, v30
	v_add3_u32 v38, v38, v43, s5
	s_nop 0
	v_addc_co_u32_e32 v31, vcc, 0, v31, vcc
	v_ashrrev_i32_e32 v37, 31, v36
	v_add_u32_e32 v40, 64, v36
	global_store_short_d16_hi v[28:29], v38, off
	global_store_short_d16_hi v[30:31], v33, off
	v_bfe_u32 v33, v27, 16, 1
	v_xor_b32_e32 v38, 0x80000000, v39
	v_add_u32_e32 v44, 0x80, v36
	v_add_u32_e32 v46, 0xc0, v36
	v_lshl_add_u64 v[36:37], v[36:37], 1, v[8:9]
	v_ashrrev_i32_e32 v41, 31, v40
	v_add3_u32 v27, v27, v33, s5
	v_bfe_u32 v33, v38, 16, 1
	v_lshl_add_u64 v[40:41], v[40:41], 1, v[8:9]
	global_store_short_d16_hi v[36:37], v27, off
	v_add3_u32 v27, v38, v33, s5
	v_bfe_u32 v33, v42, 16, 1
	v_bfe_u32 v36, v35, 16, 1
	global_store_short_d16_hi v[40:41], v27, off
	v_add3_u32 v27, v42, v33, s5
	v_ashrrev_i32_e32 v45, 31, v44
	v_add3_u32 v33, v35, v36, s5
	global_store_short_d16_hi v[28:29], v27, off offset:2
	global_store_short_d16_hi v[30:31], v33, off offset:2
	s_addk_i32 s13, 0x100
	v_ashrrev_i32_e32 v47, 31, v46
	v_lshl_add_u64 v[44:45], v[44:45], 1, v[8:9]
	v_lshl_add_u64 v[20:21], v[20:21], 0, 4
	v_lshl_add_u64 v[22:23], v[22:23], 0, 4
	v_lshl_add_u64 v[46:47], v[46:47], 1, v[8:9]
	v_xor_b32_e32 v28, 0x80000000, v32
	v_bfe_u32 v27, v34, 16, 1
	v_add3_u32 v27, v34, v27, s5
	v_bfe_u32 v29, v28, 16, 1
	global_store_short_d16_hi v[44:45], v27, off
	v_add3_u32 v27, v28, v29, s5
	global_store_short_d16_hi v[46:47], v27, off
	v_lshl_add_u64 v[30:31], v[16:17], 0, v[4:5]
	v_lshl_add_u64 v[28:29], v[14:15], 0, v[4:5]
	v_mov_b32_e32 v32, v54
	v_mov_b32_e32 v34, v70
	v_lshl_add_u64 v[36:37], v[18:19], 0, v[10:11]
	v_add_co_u32_e32 v36, vcc, s4, v36
	v_lshl_add_u64 v[14:15], v[14:15], 0, 8
	s_nop 0
	v_addc_co_u32_e32 v37, vcc, 0, v37, vcc
	v_lshl_add_u64 v[16:17], v[16:17], 0, 8
	v_lshl_add_u64 v[18:19], v[18:19], 0, 16
	v_pk_mul_f32 v[32:33], v[12:13], v[32:33] op_sel_hi:[1,0]
	s_nop 0
	v_pk_fma_f32 v[38:39], v[6:7], v[34:35], v[32:33] op_sel_hi:[1,0,1] neg_lo:[0,0,1] neg_hi:[0,0,1]
	v_pk_fma_f32 v[32:33], v[6:7], v[34:35], v[32:33] op_sel_hi:[1,0,1]
	s_nop 0
	v_mov_b32_e32 v39, v33
	global_store_dwordx2 v[36:37], v[38:39], off
	v_mov_b32_e32 v32, v55
	v_mov_b32_e32 v34, v71
	v_lshl_add_u64 v[28:29], v[24:25], 0, v[4:5]
	v_lshl_add_u64 v[30:31], v[2:3], 0, v[4:5]
	v_mov_b32_e32 v27, v86
	v_mov_b32_e32 v39, v102
	v_bfe_u32 v48, v33, 16, 1
	v_lshl_add_u64 v[2:3], v[2:3], 0, s[0:1]
	v_lshl_add_u64 v[24:25], v[24:25], 0, s[0:1]
	v_pk_mul_f32 v[40:41], v[12:13], v[32:33] op_sel_hi:[1,0]
	s_nop 0
	v_pk_fma_f32 v[42:43], v[6:7], v[34:35], v[40:41] op_sel_hi:[1,0,1] neg_lo:[0,0,1] neg_hi:[0,0,1]
	v_pk_fma_f32 v[34:35], v[6:7], v[34:35], v[40:41] op_sel_hi:[1,0,1]
	v_add3_u32 v33, v33, v48, s5
	v_mov_b32_e32 v43, v35
	global_store_dwordx2 v[36:37], v[42:43], off offset:8
	v_mov_b32_e32 v32, v103
	v_mov_b32_e32 v34, v87
	v_lshl_add_u64 v[28:29], v[20:21], 0, v[10:11]
	v_add_co_u32_e32 v28, vcc, s6, v28
	v_lshl_add_u64 v[30:31], v[22:23], 0, v[10:11]
	s_nop 0
	v_addc_co_u32_e32 v29, vcc, 0, v29, vcc
	v_bfe_u32 v43, v38, 16, 1
	v_add_u32_e32 v36, s13, v1
	v_add_co_u32_e32 v30, vcc, s6, v30
; __device__ __forceinline__ unsigned f2bf(float f) { unsigned u = __builtin_bit_cast(unsigned, f); return (u + 0x7fffu + ((u >> 16) & 1u)) >> 16; }
; #define a (*get_args())
; __device__ __forceinline__ void phase_prologue(KArgs ap, LAS unsigned char* lds, const Ctx cx) {
;     ...
;         for (int h = 0; h < 16; ++h) {
;             const float br = bre[h], bi = bim[h];
;             ((float*)(tb + TAB_BF))[((g * 64 + p) * 16 + h) * 2] = cre * br - cim * bi; ((float*)(tb + TAB_BF))[((g * 64 + p) * 16 + h) * 2 + 1] = cre * bi + cim * br;
;             BT[(g * 128 + p) * 16 + h] = (bf16_t)f2bf(cre * br - cim * bi);
;             BT[(g * 128 + 64 + p) * 16 + h] = (bf16_t)f2bf(cre * bi + cim * br);
;             CT[(g * 16 + h) * 128 + p] = (bf16_t)f2bf(a.in[I_C_RE][((size_t)(l * 32 + g) * 16 + h) * 64 + p]);
;             CT[(g * 16 + h) * 128 + 64 + p] = (bf16_t)f2bf(-a.in[I_C_IM][((size_t)(l * 32 + g) * 16 + h) * 64 + p]);
;         }
	v_add3_u32 v38, v38, v43, s5
	s_nop 0
	v_addc_co_u32_e32 v31, vcc, 0, v31, vcc
	v_ashrrev_i32_e32 v37, 31, v36
	v_add_u32_e32 v40, 64, v36
	global_store_short_d16_hi v[28:29], v38, off
	global_store_short_d16_hi v[30:31], v33, off
	v_bfe_u32 v33, v27, 16, 1
	v_xor_b32_e32 v38, 0x80000000, v39
	v_add_u32_e32 v44, 0x80, v36
	v_add_u32_e32 v46, 0xc0, v36
	v_lshl_add_u64 v[36:37], v[36:37], 1, v[8:9]
	v_ashrrev_i32_e32 v41, 31, v40
	v_add3_u32 v27, v27, v33, s5
	v_bfe_u32 v33, v38, 16, 1
	v_lshl_add_u64 v[40:41], v[40:41], 1, v[8:9]
	global_store_short_d16_hi v[36:37], v27, off
	v_add3_u32 v27, v38, v33, s5
	v_bfe_u32 v33, v42, 16, 1
	v_bfe_u32 v36, v35, 16, 1
	global_store_short_d16_hi v[40:41], v27, off
	v_add3_u32 v27, v42, v33, s5
	v_ashrrev_i32_e32 v45, 31, v44
	v_add3_u32 v33, v35, v36, s5
	global_store_short_d16_hi v[28:29], v27, off offset:2
	global_store_short_d16_hi v[30:31], v33, off offset:2
	s_addk_i32 s13, 0x100
	v_ashrrev_i32_e32 v47, 31, v46
	v_lshl_add_u64 v[44:45], v[44:45], 1, v[8:9]
	v_lshl_add_u64 v[20:21], v[20:21], 0, 4
	v_lshl_add_u64 v[22:23], v[22:23], 0, 4
	v_lshl_add_u64 v[46:47], v[46:47], 1, v[8:9]
	v_xor_b32_e32 v28, 0x80000000, v32
	v_bfe_u32 v27, v34, 16, 1
	v_add3_u32 v27, v34, v27, s5
	v_bfe_u32 v29, v28, 16, 1
	global_store_short_d16_hi v[44:45], v27, off
	v_add3_u32 v27, v28, v29, s5
	global_store_short_d16_hi v[46:47], v27, off
	v_lshl_add_u64 v[30:31], v[16:17], 0, v[4:5]
	v_lshl_add_u64 v[28:29], v[14:15], 0, v[4:5]
	v_mov_b32_e32 v32, v56
	v_mov_b32_e32 v34, v72
	v_lshl_add_u64 v[36:37], v[18:19], 0, v[10:11]
	v_add_co_u32_e32 v36, vcc, s4, v36
	v_lshl_add_u64 v[14:15], v[14:15], 0, 8
	s_nop 0
	v_addc_co_u32_e32 v37, vcc, 0, v37, vcc
	v_lshl_add_u64 v[16:17], v[16:17], 0, 8
	v_lshl_add_u64 v[18:19], v[18:19], 0, 16
	v_pk_mul_f32 v[32:33], v[12:13], v[32:33] op_sel_hi:[1,0]
	s_nop 0
	v_pk_fma_f32 v[38:39], v[6:7], v[34:35], v[32:33] op_sel_hi:[1,0,1] neg_lo:[0,0,1] neg_hi:[0,0,1]
	v_pk_fma_f32 v[32:33], v[6:7], v[34:35], v[32:33] op_sel_hi:[1,0,1]
	s_nop 0
	v_mov_b32_e32 v39, v33
	global_store_dwordx2 v[36:37], v[38:39], off
	v_mov_b32_e32 v32, v57
	v_mov_b32_e32 v34, v73
	v_lshl_add_u64 v[28:29], v[24:25], 0, v[4:5]
	v_lshl_add_u64 v[30:31], v[2:3], 0, v[4:5]
	v_mov_b32_e32 v27, v88
	v_mov_b32_e32 v39, v104
	v_bfe_u32 v48, v33, 16, 1
	v_lshl_add_u64 v[2:3], v[2:3], 0, s[0:1]
	v_lshl_add_u64 v[24:25], v[24:25], 0, s[0:1]
	v_pk_mul_f32 v[40:41], v[12:13], v[32:33] op_sel_hi:[1,0]
	s_nop 0
	v_pk_fma_f32 v[42:43], v[6:7], v[34:35], v[40:41] op_sel_hi:[1,0,1] neg_lo:[0,0,1] neg_hi:[0,0,1]
	v_pk_fma_f32 v[34:35], v[6:7], v[34:35], v[40:41] op_sel_hi:[1,0,1]
	v_add3_u32 v33, v33, v48, s5
	v_mov_b32_e32 v43, v35
	global_store_dwordx2 v[36:37], v[42:43], off offset:8
	v_mov_b32_e32 v32, v105
	v_mov_b32_e32 v34, v89
	v_lshl_add_u64 v[28:29], v[20:21], 0, v[10:11]
	v_add_co_u32_e32 v28, vcc, s6, v28
	v_lshl_add_u64 v[30:31], v[22:23], 0, v[10:11]
	s_nop 0
	v_addc_co_u32_e32 v29, vcc, 0, v29, vcc
	v_bfe_u32 v43, v38, 16, 1
	v_add_u32_e32 v36, s13, v1
	v_add_co_u32_e32 v30, vcc, s6, v30
	v_add3_u32 v38, v38, v43, s5
	s_nop 0
	v_addc_co_u32_e32 v31, vcc, 0, v31, vcc
	v_ashrrev_i32_e32 v37, 31, v36
	v_add_u32_e32 v40, 64, v36
	global_store_short_d16_hi v[28:29], v38, off
	global_store_short_d16_hi v[30:31], v33, off
	v_bfe_u32 v33, v27, 16, 1
	v_xor_b32_e32 v38, 0x80000000, v39
	v_add_u32_e32 v44, 0x80, v36
	v_add_u32_e32 v46, 0xc0, v36
	v_lshl_add_u64 v[36:37], v[36:37], 1, v[8:9]
	v_ashrrev_i32_e32 v41, 31, v40
	v_add3_u32 v27, v27, v33, s5
	v_bfe_u32 v33, v38, 16, 1
	v_lshl_add_u64 v[40:41], v[40:41], 1, v[8:9]
	global_store_short_d16_hi v[36:37], v27, off
	v_add3_u32 v27, v38, v33, s5
	v_bfe_u32 v33, v42, 16, 1
	v_bfe_u32 v36, v35, 16, 1
	global_store_short_d16_hi v[40:41], v27, off
	v_add3_u32 v27, v42, v33, s5
	v_ashrrev_i32_e32 v45, 31, v44
	v_add3_u32 v33, v35, v36, s5
	global_store_short_d16_hi v[28:29], v27, off offset:2
	global_store_short_d16_hi v[30:31], v33, off offset:2
	s_addk_i32 s13, 0x100
	v_ashrrev_i32_e32 v47, 31, v46
	v_lshl_add_u64 v[44:45], v[44:45], 1, v[8:9]
	v_lshl_add_u64 v[20:21], v[20:21], 0, 4
	v_lshl_add_u64 v[22:23], v[22:23], 0, 4
	v_lshl_add_u64 v[46:47], v[46:47], 1, v[8:9]
	v_xor_b32_e32 v28, 0x80000000, v32
	v_bfe_u32 v27, v34, 16, 1
	v_add3_u32 v27, v34, v27, s5
	v_bfe_u32 v29, v28, 16, 1
	global_store_short_d16_hi v[44:45], v27, off
	v_add3_u32 v27, v28, v29, s5
	global_store_short_d16_hi v[46:47], v27, off
	v_lshl_add_u64 v[30:31], v[16:17], 0, v[4:5]
	v_lshl_add_u64 v[28:29], v[14:15], 0, v[4:5]
	v_mov_b32_e32 v32, v58
	v_mov_b32_e32 v34, v74
	v_lshl_add_u64 v[36:37], v[18:19], 0, v[10:11]
	v_add_co_u32_e32 v36, vcc, s4, v36
	v_lshl_add_u64 v[14:15], v[14:15], 0, 8
	s_nop 0
	v_addc_co_u32_e32 v37, vcc, 0, v37, vcc
	v_lshl_add_u64 v[16:17], v[16:17], 0, 8
	v_lshl_add_u64 v[18:19], v[18:19], 0, 16
	v_pk_mul_f32 v[32:33], v[12:13], v[32:33] op_sel_hi:[1,0]
	s_nop 0
	v_pk_fma_f32 v[38:39], v[6:7], v[34:35], v[32:33] op_sel_hi:[1,0,1] neg_lo:[0,0,1] neg_hi:[0,0,1]
	v_pk_fma_f32 v[32:33], v[6:7], v[34:35], v[32:33] op_sel_hi:[1,0,1]
	s_nop 0
	v_mov_b32_e32 v39, v33
	global_store_dwordx2 v[36:37], v[38:39], off
	v_mov_b32_e32 v32, v59
	v_mov_b32_e32 v34, v75
	v_lshl_add_u64 v[28:29], v[24:25], 0, v[4:5]
	v_lshl_add_u64 v[30:31], v[2:3], 0, v[4:5]
	v_mov_b32_e32 v27, v90
	v_mov_b32_e32 v39, v106
	v_bfe_u32 v48, v33, 16, 1
	v_lshl_add_u64 v[2:3], v[2:3], 0, s[0:1]
	v_lshl_add_u64 v[24:25], v[24:25], 0, s[0:1]
	v_pk_mul_f32 v[40:41], v[12:13], v[32:33] op_sel_hi:[1,0]
	s_nop 0
	v_pk_fma_f32 v[42:43], v[6:7], v[34:35], v[40:41] op_sel_hi:[1,0,1] neg_lo:[0,0,1] neg_hi:[0,0,1]
; __device__ __forceinline__ unsigned f2bf(float f) { unsigned u = __builtin_bit_cast(unsigned, f); return (u + 0x7fffu + ((u >> 16) & 1u)) >> 16; }
; #define a (*get_args())
; __device__ __forceinline__ void phase_prologue(KArgs ap, LAS unsigned char* lds, const Ctx cx) {
;     ...
;         for (int h = 0; h < 16; ++h) {
;             const float br = bre[h], bi = bim[h];
;             ((float*)(tb + TAB_BF))[((g * 64 + p) * 16 + h) * 2] = cre * br - cim * bi; ((float*)(tb + TAB_BF))[((g * 64 + p) * 16 + h) * 2 + 1] = cre * bi + cim * br;
;             BT[(g * 128 + p) * 16 + h] = (bf16_t)f2bf(cre * br - cim * bi);
;             BT[(g * 128 + 64 + p) * 16 + h] = (bf16_t)f2bf(cre * bi + cim * br);
;             CT[(g * 16 + h) * 128 + p] = (bf16_t)f2bf(a.in[I_C_RE][((size_t)(l * 32 + g) * 16 + h) * 64 + p]);
;             CT[(g * 16 + h) * 128 + 64 + p] = (bf16_t)f2bf(-a.in[I_C_IM][((size_t)(l * 32 + g) * 16 + h) * 64 + p]);
;         }
	v_pk_fma_f32 v[34:35], v[6:7], v[34:35], v[40:41] op_sel_hi:[1,0,1]
	v_add3_u32 v33, v33, v48, s5
	v_mov_b32_e32 v43, v35
	global_store_dwordx2 v[36:37], v[42:43], off offset:8
	v_mov_b32_e32 v32, v107
	v_mov_b32_e32 v34, v91
	v_lshl_add_u64 v[28:29], v[20:21], 0, v[10:11]
	v_add_co_u32_e32 v28, vcc, s6, v28
	v_lshl_add_u64 v[30:31], v[22:23], 0, v[10:11]
	s_nop 0
	v_addc_co_u32_e32 v29, vcc, 0, v29, vcc
	v_bfe_u32 v43, v38, 16, 1
	v_add_u32_e32 v36, s13, v1
	v_add_co_u32_e32 v30, vcc, s6, v30
	v_add3_u32 v38, v38, v43, s5
	s_nop 0
	v_addc_co_u32_e32 v31, vcc, 0, v31, vcc
	v_ashrrev_i32_e32 v37, 31, v36
	v_add_u32_e32 v40, 64, v36
	global_store_short_d16_hi v[28:29], v38, off
	global_store_short_d16_hi v[30:31], v33, off
	v_bfe_u32 v33, v27, 16, 1
	v_xor_b32_e32 v38, 0x80000000, v39
	v_add_u32_e32 v44, 0x80, v36
	v_add_u32_e32 v46, 0xc0, v36
	v_lshl_add_u64 v[36:37], v[36:37], 1, v[8:9]
	v_ashrrev_i32_e32 v41, 31, v40
	v_add3_u32 v27, v27, v33, s5
	v_bfe_u32 v33, v38, 16, 1
	v_lshl_add_u64 v[40:41], v[40:41], 1, v[8:9]
	global_store_short_d16_hi v[36:37], v27, off
	v_add3_u32 v27, v38, v33, s5
	v_bfe_u32 v33, v42, 16, 1
	v_bfe_u32 v36, v35, 16, 1
	global_store_short_d16_hi v[40:41], v27, off
	v_add3_u32 v27, v42, v33, s5
	v_ashrrev_i32_e32 v45, 31, v44
	v_add3_u32 v33, v35, v36, s5
	global_store_short_d16_hi v[28:29], v27, off offset:2
	global_store_short_d16_hi v[30:31], v33, off offset:2
	s_addk_i32 s13, 0x100
	v_ashrrev_i32_e32 v47, 31, v46
	v_lshl_add_u64 v[44:45], v[44:45], 1, v[8:9]
	v_lshl_add_u64 v[20:21], v[20:21], 0, 4
	v_lshl_add_u64 v[22:23], v[22:23], 0, 4
	v_lshl_add_u64 v[46:47], v[46:47], 1, v[8:9]
	v_xor_b32_e32 v28, 0x80000000, v32
	v_bfe_u32 v27, v34, 16, 1
	v_add3_u32 v27, v34, v27, s5
	v_bfe_u32 v29, v28, 16, 1
	global_store_short_d16_hi v[44:45], v27, off
	v_add3_u32 v27, v28, v29, s5
	global_store_short_d16_hi v[46:47], v27, off
	v_lshl_add_u64 v[30:31], v[16:17], 0, v[4:5]
	v_lshl_add_u64 v[28:29], v[14:15], 0, v[4:5]
	v_mov_b32_e32 v32, v60
	v_mov_b32_e32 v34, v76
	v_lshl_add_u64 v[36:37], v[18:19], 0, v[10:11]
	v_add_co_u32_e32 v36, vcc, s4, v36
	v_lshl_add_u64 v[14:15], v[14:15], 0, 8
	s_nop 0
	v_addc_co_u32_e32 v37, vcc, 0, v37, vcc
	v_lshl_add_u64 v[16:17], v[16:17], 0, 8
	v_lshl_add_u64 v[18:19], v[18:19], 0, 16
	v_pk_mul_f32 v[32:33], v[12:13], v[32:33] op_sel_hi:[1,0]
	s_nop 0
	v_pk_fma_f32 v[38:39], v[6:7], v[34:35], v[32:33] op_sel_hi:[1,0,1] neg_lo:[0,0,1] neg_hi:[0,0,1]
	v_pk_fma_f32 v[32:33], v[6:7], v[34:35], v[32:33] op_sel_hi:[1,0,1]
	s_nop 0
	v_mov_b32_e32 v39, v33
	global_store_dwordx2 v[36:37], v[38:39], off
	v_mov_b32_e32 v32, v61
	v_mov_b32_e32 v34, v77
	v_lshl_add_u64 v[28:29], v[24:25], 0, v[4:5]
	v_lshl_add_u64 v[30:31], v[2:3], 0, v[4:5]
	v_mov_b32_e32 v27, v92
	v_mov_b32_e32 v39, v108
	v_bfe_u32 v48, v33, 16, 1
	v_lshl_add_u64 v[2:3], v[2:3], 0, s[0:1]
	v_lshl_add_u64 v[24:25], v[24:25], 0, s[0:1]
	v_pk_mul_f32 v[40:41], v[12:13], v[32:33] op_sel_hi:[1,0]
	s_nop 0
	v_pk_fma_f32 v[42:43], v[6:7], v[34:35], v[40:41] op_sel_hi:[1,0,1] neg_lo:[0,0,1] neg_hi:[0,0,1]
	v_pk_fma_f32 v[34:35], v[6:7], v[34:35], v[40:41] op_sel_hi:[1,0,1]
	v_add3_u32 v33, v33, v48, s5
	v_mov_b32_e32 v43, v35
	global_store_dwordx2 v[36:37], v[42:43], off offset:8
	v_mov_b32_e32 v32, v109
	v_mov_b32_e32 v34, v93
	v_lshl_add_u64 v[28:29], v[20:21], 0, v[10:11]
	v_add_co_u32_e32 v28, vcc, s6, v28
	v_lshl_add_u64 v[30:31], v[22:23], 0, v[10:11]
	s_nop 0
	v_addc_co_u32_e32 v29, vcc, 0, v29, vcc
	v_bfe_u32 v43, v38, 16, 1
	v_add_u32_e32 v36, s13, v1
	v_add_co_u32_e32 v30, vcc, s6, v30
	v_add3_u32 v38, v38, v43, s5
	s_nop 0
	v_addc_co_u32_e32 v31, vcc, 0, v31, vcc
	v_ashrrev_i32_e32 v37, 31, v36
	v_add_u32_e32 v40, 64, v36
	global_store_short_d16_hi v[28:29], v38, off
	global_store_short_d16_hi v[30:31], v33, off
	v_bfe_u32 v33, v27, 16, 1
	v_xor_b32_e32 v38, 0x80000000, v39
	v_add_u32_e32 v44, 0x80, v36
	v_add_u32_e32 v46, 0xc0, v36
	v_lshl_add_u64 v[36:37], v[36:37], 1, v[8:9]
	v_ashrrev_i32_e32 v41, 31, v40
	v_add3_u32 v27, v27, v33, s5
	v_bfe_u32 v33, v38, 16, 1
	v_lshl_add_u64 v[40:41], v[40:41], 1, v[8:9]
	global_store_short_d16_hi v[36:37], v27, off
	v_add3_u32 v27, v38, v33, s5
	v_bfe_u32 v33, v42, 16, 1
	v_bfe_u32 v36, v35, 16, 1
	global_store_short_d16_hi v[40:41], v27, off
	v_add3_u32 v27, v42, v33, s5
	v_ashrrev_i32_e32 v45, 31, v44
	v_add3_u32 v33, v35, v36, s5
	global_store_short_d16_hi v[28:29], v27, off offset:2
	global_store_short_d16_hi v[30:31], v33, off offset:2
	s_addk_i32 s13, 0x100
	v_ashrrev_i32_e32 v47, 31, v46
	v_lshl_add_u64 v[44:45], v[44:45], 1, v[8:9]
	v_lshl_add_u64 v[20:21], v[20:21], 0, 4
	v_lshl_add_u64 v[22:23], v[22:23], 0, 4
	v_lshl_add_u64 v[46:47], v[46:47], 1, v[8:9]
	v_xor_b32_e32 v28, 0x80000000, v32
	v_bfe_u32 v27, v34, 16, 1
	v_add3_u32 v27, v34, v27, s5
	v_bfe_u32 v29, v28, 16, 1
	global_store_short_d16_hi v[44:45], v27, off
	v_add3_u32 v27, v28, v29, s5
	global_store_short_d16_hi v[46:47], v27, off
	v_lshl_add_u64 v[30:31], v[16:17], 0, v[4:5]
	v_lshl_add_u64 v[28:29], v[14:15], 0, v[4:5]
	v_mov_b32_e32 v32, v62
	v_mov_b32_e32 v34, v78
	v_lshl_add_u64 v[36:37], v[18:19], 0, v[10:11]
	v_add_co_u32_e32 v36, vcc, s4, v36
	v_lshl_add_u64 v[14:15], v[14:15], 0, 8
	s_nop 0
	v_addc_co_u32_e32 v37, vcc, 0, v37, vcc
	v_lshl_add_u64 v[16:17], v[16:17], 0, 8
	v_lshl_add_u64 v[18:19], v[18:19], 0, 16
	v_pk_mul_f32 v[32:33], v[12:13], v[32:33] op_sel_hi:[1,0]
	s_nop 0
	v_pk_fma_f32 v[38:39], v[6:7], v[34:35], v[32:33] op_sel_hi:[1,0,1] neg_lo:[0,0,1] neg_hi:[0,0,1]
; __device__ __forceinline__ unsigned f2bf(float f) { unsigned u = __builtin_bit_cast(unsigned, f); return (u + 0x7fffu + ((u >> 16) & 1u)) >> 16; }
; #define a (*get_args())
; __device__ __forceinline__ void phase_prologue(KArgs ap, LAS unsigned char* lds, const Ctx cx) {
;     ...
;         for (int h = 0; h < 16; ++h) {
;             const float br = bre[h], bi = bim[h];
;             ((float*)(tb + TAB_BF))[((g * 64 + p) * 16 + h) * 2] = cre * br - cim * bi; ((float*)(tb + TAB_BF))[((g * 64 + p) * 16 + h) * 2 + 1] = cre * bi + cim * br;
;             BT[(g * 128 + p) * 16 + h] = (bf16_t)f2bf(cre * br - cim * bi);
;             BT[(g * 128 + 64 + p) * 16 + h] = (bf16_t)f2bf(cre * bi + cim * br);
;             CT[(g * 16 + h) * 128 + p] = (bf16_t)f2bf(a.in[I_C_RE][((size_t)(l * 32 + g) * 16 + h) * 64 + p]);
;             CT[(g * 16 + h) * 128 + 64 + p] = (bf16_t)f2bf(-a.in[I_C_IM][((size_t)(l * 32 + g) * 16 + h) * 64 + p]);
;         }
	v_pk_fma_f32 v[32:33], v[6:7], v[34:35], v[32:33] op_sel_hi:[1,0,1]
	s_nop 0
	v_mov_b32_e32 v39, v33
	global_store_dwordx2 v[36:37], v[38:39], off
	v_mov_b32_e32 v32, v63
	v_mov_b32_e32 v34, v79
	v_lshl_add_u64 v[28:29], v[24:25], 0, v[4:5]
	v_lshl_add_u64 v[30:31], v[2:3], 0, v[4:5]
	v_mov_b32_e32 v27, v94
	v_mov_b32_e32 v39, v110
	v_bfe_u32 v48, v33, 16, 1
	v_lshl_add_u64 v[2:3], v[2:3], 0, s[0:1]
	v_lshl_add_u64 v[24:25], v[24:25], 0, s[0:1]
	v_pk_mul_f32 v[40:41], v[12:13], v[32:33] op_sel_hi:[1,0]
	s_nop 0
	v_pk_fma_f32 v[42:43], v[6:7], v[34:35], v[40:41] op_sel_hi:[1,0,1] neg_lo:[0,0,1] neg_hi:[0,0,1]
	v_pk_fma_f32 v[34:35], v[6:7], v[34:35], v[40:41] op_sel_hi:[1,0,1]
	v_add3_u32 v33, v33, v48, s5
	v_mov_b32_e32 v43, v35
	global_store_dwordx2 v[36:37], v[42:43], off offset:8
	v_mov_b32_e32 v32, v111
	v_mov_b32_e32 v34, v95
	v_lshl_add_u64 v[28:29], v[20:21], 0, v[10:11]
	v_add_co_u32_e32 v28, vcc, s6, v28
	v_lshl_add_u64 v[30:31], v[22:23], 0, v[10:11]
	s_nop 0
	v_addc_co_u32_e32 v29, vcc, 0, v29, vcc
	v_bfe_u32 v43, v38, 16, 1
	v_add_u32_e32 v36, s13, v1
	v_add_co_u32_e32 v30, vcc, s6, v30
	v_add3_u32 v38, v38, v43, s5
	s_nop 0
	v_addc_co_u32_e32 v31, vcc, 0, v31, vcc
	v_ashrrev_i32_e32 v37, 31, v36
	v_add_u32_e32 v40, 64, v36
	global_store_short_d16_hi v[28:29], v38, off
	global_store_short_d16_hi v[30:31], v33, off
	v_bfe_u32 v33, v27, 16, 1
	v_xor_b32_e32 v38, 0x80000000, v39
	v_add_u32_e32 v44, 0x80, v36
	v_add_u32_e32 v46, 0xc0, v36
	v_lshl_add_u64 v[36:37], v[36:37], 1, v[8:9]
	v_ashrrev_i32_e32 v41, 31, v40
	v_add3_u32 v27, v27, v33, s5
	v_bfe_u32 v33, v38, 16, 1
	v_lshl_add_u64 v[40:41], v[40:41], 1, v[8:9]
	global_store_short_d16_hi v[36:37], v27, off
	v_add3_u32 v27, v38, v33, s5
	v_bfe_u32 v33, v42, 16, 1
	v_bfe_u32 v36, v35, 16, 1
	global_store_short_d16_hi v[40:41], v27, off
	v_add3_u32 v27, v42, v33, s5
	v_ashrrev_i32_e32 v45, 31, v44
	v_add3_u32 v33, v35, v36, s5
	global_store_short_d16_hi v[28:29], v27, off offset:2
	global_store_short_d16_hi v[30:31], v33, off offset:2
	s_addk_i32 s13, 0x100
	v_ashrrev_i32_e32 v47, 31, v46
	v_lshl_add_u64 v[44:45], v[44:45], 1, v[8:9]
	v_lshl_add_u64 v[20:21], v[20:21], 0, 4
	v_lshl_add_u64 v[22:23], v[22:23], 0, 4
	v_lshl_add_u64 v[46:47], v[46:47], 1, v[8:9]
	v_xor_b32_e32 v28, 0x80000000, v32
	v_bfe_u32 v27, v34, 16, 1
	v_add3_u32 v27, v34, v27, s5
	v_bfe_u32 v29, v28, 16, 1
	global_store_short_d16_hi v[44:45], v27, off
	v_add3_u32 v27, v28, v29, s5
	global_store_short_d16_hi v[46:47], v27, off
	v_lshl_add_u64 v[30:31], v[16:17], 0, v[4:5]
	v_lshl_add_u64 v[28:29], v[14:15], 0, v[4:5]
	v_mov_b32_e32 v32, v64
	v_mov_b32_e32 v34, v80
	v_lshl_add_u64 v[36:37], v[18:19], 0, v[10:11]
	v_add_co_u32_e32 v36, vcc, s4, v36
	v_lshl_add_u64 v[14:15], v[14:15], 0, 8
	s_nop 0
	v_addc_co_u32_e32 v37, vcc, 0, v37, vcc
	v_lshl_add_u64 v[16:17], v[16:17], 0, 8
	v_lshl_add_u64 v[18:19], v[18:19], 0, 16
	v_pk_mul_f32 v[32:33], v[12:13], v[32:33] op_sel_hi:[1,0]
	s_nop 0
	v_pk_fma_f32 v[38:39], v[6:7], v[34:35], v[32:33] op_sel_hi:[1,0,1] neg_lo:[0,0,1] neg_hi:[0,0,1]
	v_pk_fma_f32 v[32:33], v[6:7], v[34:35], v[32:33] op_sel_hi:[1,0,1]
	s_nop 0
	v_mov_b32_e32 v39, v33
	global_store_dwordx2 v[36:37], v[38:39], off
	v_mov_b32_e32 v32, v65
	v_mov_b32_e32 v34, v81
	v_lshl_add_u64 v[28:29], v[24:25], 0, v[4:5]
	v_lshl_add_u64 v[30:31], v[2:3], 0, v[4:5]
	v_mov_b32_e32 v27, v96
	v_mov_b32_e32 v39, v112
	v_bfe_u32 v48, v33, 16, 1
	v_lshl_add_u64 v[2:3], v[2:3], 0, s[0:1]
	v_lshl_add_u64 v[24:25], v[24:25], 0, s[0:1]
	v_pk_mul_f32 v[40:41], v[12:13], v[32:33] op_sel_hi:[1,0]
	s_nop 0
	v_pk_fma_f32 v[42:43], v[6:7], v[34:35], v[40:41] op_sel_hi:[1,0,1] neg_lo:[0,0,1] neg_hi:[0,0,1]
	v_pk_fma_f32 v[34:35], v[6:7], v[34:35], v[40:41] op_sel_hi:[1,0,1]
	v_add3_u32 v33, v33, v48, s5
	v_mov_b32_e32 v43, v35
	global_store_dwordx2 v[36:37], v[42:43], off offset:8
	v_mov_b32_e32 v32, v113
	v_mov_b32_e32 v34, v97
	v_lshl_add_u64 v[28:29], v[20:21], 0, v[10:11]
	v_add_co_u32_e32 v28, vcc, s6, v28
	v_lshl_add_u64 v[30:31], v[22:23], 0, v[10:11]
	s_nop 0
	v_addc_co_u32_e32 v29, vcc, 0, v29, vcc
	v_bfe_u32 v43, v38, 16, 1
	v_add_u32_e32 v36, s13, v1
	v_add_co_u32_e32 v30, vcc, s6, v30
	v_add3_u32 v38, v38, v43, s5
	s_nop 0
	v_addc_co_u32_e32 v31, vcc, 0, v31, vcc
	v_ashrrev_i32_e32 v37, 31, v36
	v_add_u32_e32 v40, 64, v36
	global_store_short_d16_hi v[28:29], v38, off
	global_store_short_d16_hi v[30:31], v33, off
	v_bfe_u32 v33, v27, 16, 1
	v_xor_b32_e32 v38, 0x80000000, v39
	v_add_u32_e32 v44, 0x80, v36
	v_add_u32_e32 v46, 0xc0, v36
	v_lshl_add_u64 v[36:37], v[36:37], 1, v[8:9]
	v_ashrrev_i32_e32 v41, 31, v40
	v_add3_u32 v27, v27, v33, s5
	v_bfe_u32 v33, v38, 16, 1
	v_lshl_add_u64 v[40:41], v[40:41], 1, v[8:9]
	global_store_short_d16_hi v[36:37], v27, off
	v_add3_u32 v27, v38, v33, s5
	v_bfe_u32 v33, v42, 16, 1
	v_bfe_u32 v36, v35, 16, 1
	global_store_short_d16_hi v[40:41], v27, off
	v_add3_u32 v27, v42, v33, s5
	v_ashrrev_i32_e32 v45, 31, v44
	v_add3_u32 v33, v35, v36, s5
	global_store_short_d16_hi v[28:29], v27, off offset:2
	global_store_short_d16_hi v[30:31], v33, off offset:2
	s_addk_i32 s13, 0x100
	v_ashrrev_i32_e32 v47, 31, v46
	v_lshl_add_u64 v[44:45], v[44:45], 1, v[8:9]
	v_lshl_add_u64 v[20:21], v[20:21], 0, 4
	v_lshl_add_u64 v[22:23], v[22:23], 0, 4
	v_lshl_add_u64 v[46:47], v[46:47], 1, v[8:9]
	v_xor_b32_e32 v28, 0x80000000, v32
	v_bfe_u32 v27, v34, 16, 1
	v_add3_u32 v27, v34, v27, s5
	v_bfe_u32 v29, v28, 16, 1
	global_store_short_d16_hi v[44:45], v27, off
	v_add3_u32 v27, v28, v29, s5
	global_store_short_d16_hi v[46:47], v27, off
